# adds attention PV MFMA order: each 32x32 output accumulator gets its four MFMAs back to back (first-half V waits recounted)
# baseline (speedup 1.0000x reference)
.LBB0_91:
	s_waitcnt lgkmcnt(14)
	v_mfma_f32_32x32x16_bf16 v[32:47], v[164:167], v[208:211], v[32:47]
	v_exp_f32_e32 v128, v128
	v_exp_f32_e32 v129, v129
	ds_read_b64_tr_b16 v[92:93], v213 offset:32768
	ds_read_b64_tr_b16 v[94:95], v213 offset:33280
	s_waitcnt lgkmcnt(12)
	v_mfma_f32_32x32x16_bf16 v[32:47], v[156:159], v[96:99], v[32:47]
	v_exp_f32_e32 v130, v130
	v_exp_f32_e32 v131, v131
	ds_read_b64_tr_b16 v[96:97], v213 offset:33792
	ds_read_b64_tr_b16 v[98:99], v213 offset:34304
	v_add_u32_e32 v176, s25, v224
	ds_read_b128 v[80:83], v176
	ds_read_b128 v[196:199], v176 offset:512
	s_waitcnt lgkmcnt(12)
	v_mfma_f32_32x32x16_bf16 v[32:47], v[148:151], v[104:107], v[32:47]
	v_exp_f32_e32 v132, v132
	v_exp_f32_e32 v133, v133
	ds_read_b64_tr_b16 v[104:105], v213 offset:34816
	ds_read_b64_tr_b16 v[106:107], v213 offset:35328
	ds_read_b128 v[200:203], v176 offset:2048
	ds_read_b128 v[192:195], v176 offset:2560
	s_waitcnt lgkmcnt(12)
	v_mfma_f32_32x32x16_bf16 v[32:47], v[144:147], v[84:87], v[32:47]
	v_exp_f32_e32 v134, v134
	v_exp_f32_e32 v135, v135
	ds_read_b64_tr_b16 v[84:85], v213 offset:35840
	ds_read_b64_tr_b16 v[86:87], v213 offset:36352
	ds_read_b128 v[188:191], v176 offset:4096
	ds_read_b128 v[184:187], v176 offset:4608
	s_waitcnt lgkmcnt(14)
	v_mfma_f32_32x32x16_bf16 v[48:63], v[164:167], v[204:207], v[48:63]
	v_exp_f32_e32 v136, v136
	v_exp_f32_e32 v137, v137
	ds_read_b64_tr_b16 v[204:205], v213 offset:36864
	ds_read_b64_tr_b16 v[206:207], v213 offset:37376
	ds_read_b128 v[180:183], v176 offset:6144
	ds_read_b128 v[176:179], v176 offset:6656
	v_mfma_f32_32x32x16_bf16 v[48:63], v[156:159], v[100:103], v[48:63]
	v_exp_f32_e32 v138, v138
	v_exp_f32_e32 v139, v139
	ds_read_b64_tr_b16 v[100:101], v213 offset:37888
	ds_read_b64_tr_b16 v[102:103], v213 offset:38400
	v_mfma_f32_32x32x16_bf16 v[48:63], v[148:151], v[108:111], v[48:63]
	v_exp_f32_e32 v140, v140
	v_exp_f32_e32 v141, v141
	ds_read_b64_tr_b16 v[108:109], v213 offset:38912
	ds_read_b64_tr_b16 v[110:111], v213 offset:39424
	v_mfma_f32_32x32x16_bf16 v[48:63], v[144:147], v[88:91], v[48:63]
	v_exp_f32_e32 v142, v142
	v_exp_f32_e32 v143, v143
	ds_read_b64_tr_b16 v[88:89], v213 offset:39936
	ds_read_b64_tr_b16 v[90:91], v213 offset:40448
	s_waitcnt lgkmcnt(14)
	v_mfma_f32_32x32x16_bf16 v[16:31], v[164:167], v[92:95], v[16:31]
	v_exp_f32_e32 v112, v112
	v_exp_f32_e32 v113, v113
	v_mfma_f32_32x32x16_bf16 v[16:31], v[156:159], v[96:99], v[16:31]
	v_exp_f32_e32 v114, v114
	v_exp_f32_e32 v115, v115
	v_mfma_f32_32x32x16_bf16 v[16:31], v[148:151], v[104:107], v[16:31]
	v_exp_f32_e32 v116, v116
	v_exp_f32_e32 v117, v117
	s_waitcnt lgkmcnt(12)
	v_mfma_f32_32x32x16_bf16 v[16:31], v[144:147], v[84:87], v[16:31]
	v_exp_f32_e32 v118, v118
	v_exp_f32_e32 v119, v119
	s_waitcnt lgkmcnt(8)
	v_mfma_f32_32x32x16_bf16 v[0:15], v[164:167], v[204:207], v[0:15]
	v_exp_f32_e32 v120, v120
	v_exp_f32_e32 v121, v121
	s_waitcnt lgkmcnt(4)
	v_mfma_f32_32x32x16_bf16 v[0:15], v[156:159], v[100:103], v[0:15]
	v_exp_f32_e32 v122, v122
	v_exp_f32_e32 v123, v123
	s_waitcnt lgkmcnt(2)
	v_mfma_f32_32x32x16_bf16 v[0:15], v[148:151], v[108:111], v[0:15]
	v_exp_f32_e32 v124, v124
	v_exp_f32_e32 v125, v125
	s_waitcnt lgkmcnt(0)
	v_mfma_f32_32x32x16_bf16 v[0:15], v[144:147], v[88:91], v[0:15]
	v_exp_f32_e32 v126, v126
	v_exp_f32_e32 v127, v127
	s_waitcnt vmcnt(3) lgkmcnt(0)
	s_barrier
	s_andn2_b64 vcc, exec, s[38:39]
	v_add_u32_e32 v213, s17, v226
	s_cbranch_vccnz .LBB0_93
	s_waitcnt lgkmcnt(0)
	ds_read_b128 v[84:87], v213 offset:96
	ds_read_b128 v[88:91], v213 offset:64
	ds_read_b128 v[92:95], v213 offset:32
	ds_read_b128 v[96:99], v213
	s_waitcnt lgkmcnt(3)
	v_pk_mul_f32 v[44:45], v[44:45], v[84:85]
	s_waitcnt lgkmcnt(2)
	v_pk_mul_f32 v[40:41], v[40:41], v[88:89]
	s_waitcnt lgkmcnt(1)
	v_pk_mul_f32 v[36:37], v[36:37], v[92:93]
	v_pk_mul_f32 v[46:47], v[46:47], v[86:87]
	v_pk_mul_f32 v[42:43], v[42:43], v[90:91]
	v_pk_mul_f32 v[38:39], v[38:39], v[94:95]
	s_waitcnt lgkmcnt(0)
	v_pk_mul_f32 v[34:35], v[34:35], v[98:99]
	v_pk_mul_f32 v[32:33], v[32:33], v[96:97]
	v_pk_mul_f32 v[60:61], v[60:61], v[84:85]
	v_pk_mul_f32 v[56:57], v[56:57], v[88:89]
	v_pk_mul_f32 v[52:53], v[52:53], v[92:93]
	v_pk_mul_f32 v[62:63], v[62:63], v[86:87]
	v_pk_mul_f32 v[58:59], v[58:59], v[90:91]
	v_pk_mul_f32 v[54:55], v[54:55], v[94:95]
	v_pk_mul_f32 v[50:51], v[50:51], v[98:99]
	v_pk_mul_f32 v[48:49], v[48:49], v[96:97]
	v_pk_mul_f32 v[28:29], v[28:29], v[84:85]
	v_pk_mul_f32 v[24:25], v[24:25], v[88:89]
	v_pk_mul_f32 v[20:21], v[20:21], v[92:93]
	v_pk_mul_f32 v[30:31], v[30:31], v[86:87]
	v_pk_mul_f32 v[26:27], v[26:27], v[90:91]
	v_pk_mul_f32 v[22:23], v[22:23], v[94:95]
	v_pk_mul_f32 v[18:19], v[18:19], v[98:99]
	v_pk_mul_f32 v[16:17], v[16:17], v[96:97]
	v_pk_mul_f32 v[12:13], v[12:13], v[84:85]
	v_pk_mul_f32 v[8:9], v[8:9], v[88:89]
	v_pk_mul_f32 v[4:5], v[4:5], v[92:93]
	v_pk_mul_f32 v[14:15], v[14:15], v[86:87]
	v_pk_mul_f32 v[10:11], v[10:11], v[90:91]
	v_pk_mul_f32 v[6:7], v[6:7], v[94:95]
	v_pk_mul_f32 v[2:3], v[2:3], v[98:99]
	v_pk_mul_f32 v[0:1], v[0:1], v[96:97]

.LBB0_94:
	s_waitcnt lgkmcnt(14)
	v_mfma_f32_32x32x16_bf16 v[32:47], v[164:167], v[204:207], v[32:47]
	v_exp_f32_e32 v96, v96
	v_exp_f32_e32 v97, v97
	ds_read_b64_tr_b16 v[124:125], v228 offset:32768
	ds_read_b64_tr_b16 v[126:127], v228 offset:33280
	s_waitcnt lgkmcnt(12)
	v_mfma_f32_32x32x16_bf16 v[32:47], v[156:159], v[128:131], v[32:47]
	v_exp_f32_e32 v98, v98
	v_exp_f32_e32 v99, v99
	ds_read_b64_tr_b16 v[128:129], v228 offset:33792
	ds_read_b64_tr_b16 v[130:131], v228 offset:34304
	v_add_u32_e32 v176, s21, v224
	ds_read_b128 v[204:207], v176
	ds_read_b128 v[200:203], v176 offset:512
	s_waitcnt lgkmcnt(12)
	v_mfma_f32_32x32x16_bf16 v[32:47], v[148:151], v[136:139], v[32:47]
	v_exp_f32_e32 v100, v100
	v_exp_f32_e32 v101, v101
	ds_read_b64_tr_b16 v[136:137], v228 offset:34816
	ds_read_b64_tr_b16 v[138:139], v228 offset:35328
	ds_read_b128 v[196:199], v176 offset:2048
	ds_read_b128 v[192:195], v176 offset:2560
	s_waitcnt lgkmcnt(12)
	v_mfma_f32_32x32x16_bf16 v[32:47], v[144:147], v[116:119], v[32:47]
	v_exp_f32_e32 v102, v102
	v_exp_f32_e32 v103, v103
	ds_read_b64_tr_b16 v[116:117], v228 offset:35840
	ds_read_b64_tr_b16 v[118:119], v228 offset:36352
	ds_read_b128 v[188:191], v176 offset:4096
	ds_read_b128 v[184:187], v176 offset:4608
	s_waitcnt lgkmcnt(14)
	v_mfma_f32_32x32x16_bf16 v[48:63], v[164:167], v[208:211], v[48:63]
	v_exp_f32_e32 v104, v104
	v_exp_f32_e32 v105, v105
	ds_read_b64_tr_b16 v[140:141], v228 offset:36864
	ds_read_b64_tr_b16 v[142:143], v228 offset:37376
	ds_read_b128 v[180:183], v176 offset:6144
	ds_read_b128 v[176:179], v176 offset:6656
	v_mfma_f32_32x32x16_bf16 v[48:63], v[156:159], v[132:135], v[48:63]
	v_exp_f32_e32 v106, v106
	v_exp_f32_e32 v107, v107
	ds_read_b64_tr_b16 v[132:133], v228 offset:37888
	ds_read_b64_tr_b16 v[134:135], v228 offset:38400
	v_mfma_f32_32x32x16_bf16 v[48:63], v[148:151], v[112:115], v[48:63]
	v_exp_f32_e32 v108, v108
	v_exp_f32_e32 v109, v109
	ds_read_b64_tr_b16 v[112:113], v228 offset:38912
	ds_read_b64_tr_b16 v[114:115], v228 offset:39424
	v_mfma_f32_32x32x16_bf16 v[48:63], v[144:147], v[120:123], v[48:63]
	v_exp_f32_e32 v110, v110
	v_exp_f32_e32 v111, v111
	ds_read_b64_tr_b16 v[120:121], v228 offset:39936
	ds_read_b64_tr_b16 v[122:123], v228 offset:40448
	s_waitcnt lgkmcnt(14)
	v_mfma_f32_32x32x16_bf16 v[16:31], v[164:167], v[124:127], v[16:31]
	v_exp_f32_e32 v80, v80
	v_exp_f32_e32 v81, v81
	v_mfma_f32_32x32x16_bf16 v[16:31], v[156:159], v[128:131], v[16:31]
	v_exp_f32_e32 v82, v82
	v_exp_f32_e32 v83, v83
	v_mfma_f32_32x32x16_bf16 v[16:31], v[148:151], v[136:139], v[16:31]
	v_exp_f32_e32 v84, v84
	v_exp_f32_e32 v85, v85
	s_waitcnt lgkmcnt(12)
	v_mfma_f32_32x32x16_bf16 v[16:31], v[144:147], v[116:119], v[16:31]
	v_exp_f32_e32 v86, v86
	v_exp_f32_e32 v87, v87
	s_waitcnt lgkmcnt(8)
	v_mfma_f32_32x32x16_bf16 v[0:15], v[164:167], v[140:143], v[0:15]
	v_exp_f32_e32 v88, v88
	v_exp_f32_e32 v89, v89
	s_waitcnt lgkmcnt(4)
	v_mfma_f32_32x32x16_bf16 v[0:15], v[156:159], v[132:135], v[0:15]
	v_exp_f32_e32 v90, v90
	v_exp_f32_e32 v91, v91
	s_waitcnt lgkmcnt(2)
	v_mfma_f32_32x32x16_bf16 v[0:15], v[148:151], v[112:115], v[0:15]
	v_exp_f32_e32 v92, v92
	v_exp_f32_e32 v93, v93
	s_waitcnt lgkmcnt(0)
	v_mfma_f32_32x32x16_bf16 v[0:15], v[144:147], v[120:123], v[0:15]
	v_exp_f32_e32 v94, v94
	v_exp_f32_e32 v95, v95
	s_waitcnt vmcnt(3) lgkmcnt(0)
	s_barrier
	s_andn2_b64 vcc, exec, s[38:39]
	s_cbranch_vccnz .LBB0_96
	s_waitcnt lgkmcnt(0)
	ds_read_b128 v[112:115], v213 offset:96
	ds_read_b128 v[116:119], v213 offset:64
	ds_read_b128 v[120:123], v213 offset:32
	ds_read_b128 v[124:127], v213
	s_waitcnt lgkmcnt(3)
	v_pk_mul_f32 v[44:45], v[44:45], v[112:113]
	s_waitcnt lgkmcnt(2)
	v_pk_mul_f32 v[40:41], v[40:41], v[116:117]
	s_waitcnt lgkmcnt(1)
	v_pk_mul_f32 v[36:37], v[36:37], v[120:121]
	v_pk_mul_f32 v[46:47], v[46:47], v[114:115]
	v_pk_mul_f32 v[42:43], v[42:43], v[118:119]
	v_pk_mul_f32 v[38:39], v[38:39], v[122:123]
	s_waitcnt lgkmcnt(0)
	v_pk_mul_f32 v[34:35], v[34:35], v[126:127]
	v_pk_mul_f32 v[32:33], v[32:33], v[124:125]
	v_pk_mul_f32 v[60:61], v[60:61], v[112:113]
	v_pk_mul_f32 v[56:57], v[56:57], v[116:117]
	v_pk_mul_f32 v[52:53], v[52:53], v[120:121]
	v_pk_mul_f32 v[62:63], v[62:63], v[114:115]
	v_pk_mul_f32 v[58:59], v[58:59], v[118:119]
	v_pk_mul_f32 v[54:55], v[54:55], v[122:123]
	v_pk_mul_f32 v[50:51], v[50:51], v[126:127]
	v_pk_mul_f32 v[48:49], v[48:49], v[124:125]
	v_pk_mul_f32 v[28:29], v[28:29], v[112:113]
	v_pk_mul_f32 v[24:25], v[24:25], v[116:117]
	v_pk_mul_f32 v[20:21], v[20:21], v[120:121]
	v_pk_mul_f32 v[30:31], v[30:31], v[114:115]
	v_pk_mul_f32 v[26:27], v[26:27], v[118:119]
	v_pk_mul_f32 v[22:23], v[22:23], v[122:123]
	v_pk_mul_f32 v[18:19], v[18:19], v[126:127]
	v_pk_mul_f32 v[16:17], v[16:17], v[124:125]
	v_pk_mul_f32 v[12:13], v[12:13], v[112:113]
	v_pk_mul_f32 v[8:9], v[8:9], v[116:117]
	v_pk_mul_f32 v[4:5], v[4:5], v[120:121]
	v_pk_mul_f32 v[14:15], v[14:15], v[114:115]
	v_pk_mul_f32 v[10:11], v[10:11], v[118:119]
	v_pk_mul_f32 v[6:7], v[6:7], v[122:123]
	v_pk_mul_f32 v[2:3], v[2:3], v[126:127]
	v_pk_mul_f32 v[0:1], v[0:1], v[124:125]
